# out-proj fused-norm epilogue (final layer): the two bf16 residual loads of each row block issued together, one wait instead of two
# speedup vs baseline: 1.0026x; 1.0026x over previous
.LBB0_1231:
	s_lshl_b32 s9, s8, 8
	v_add_u32_e32 v130, s9, v1
	v_ashrrev_i32_e32 v131, 31, v130
	s_lshl_b32 s10, s6, 8
	v_lshlrev_b64 v[146:147], 10, v[130:131]
	s_ashr_i32 s11, s10, 31
	v_readlane_b32 s12, v253, 59
	v_lshl_or_b32 v174, v138, 3, s30
	v_lshl_add_u64 v[138:139], v[146:147], 0, s[10:11]
	v_readlane_b32 s13, v253, 60
	v_readlane_b32 s36, v251, 16
	v_or_b32_e32 v138, v138, v174
	v_cndmask_b32_e64 v130, 0, 1, s[12:13]
	v_readlane_b32 s50, v251, 30
	v_readlane_b32 s51, v251, 31
	s_mov_b64 s[4:5], -1
	v_cmp_ne_u32_e64 s[0:1], 1, v130
	s_andn2_b64 vcc, exec, s[12:13]
	v_lshl_add_u64 v[148:149], v[138:139], 1, s[50:51]
	s_barrier
	v_readlane_b32 s37, v251, 17
	v_readlane_b32 s38, v251, 18
	v_readlane_b32 s39, v251, 19
	v_readlane_b32 s40, v251, 20
	v_readlane_b32 s41, v251, 21
	v_readlane_b32 s42, v251, 22
	v_readlane_b32 s43, v251, 23
	v_readlane_b32 s44, v251, 24
	v_readlane_b32 s45, v251, 25
	v_readlane_b32 s46, v251, 26
	v_readlane_b32 s47, v251, 27
	v_readlane_b32 s48, v251, 28
	v_readlane_b32 s49, v251, 29
	s_cbranch_vccnz .LBB0_1233
	global_load_dwordx4 v[134:137], v[148:149], off
	global_load_dwordx4 v[142:145], v[148:149], off offset:256
	s_mov_b64 s[4:5], 0
	s_waitcnt vmcnt(0)
	v_lshlrev_b32_e32 v130, 16, v134
	v_and_b32_e32 v131, 0xffff0000, v134
	v_lshlrev_b32_e32 v132, 16, v135
	v_and_b32_e32 v133, 0xffff0000, v135
	v_lshlrev_b32_e32 v134, 16, v136
	v_and_b32_e32 v135, 0xffff0000, v136
	v_lshlrev_b32_e32 v136, 16, v137
	v_and_b32_e32 v137, 0xffff0000, v137

.LBB0_1235:
	s_and_b64 vcc, exec, s[0:1]
	s_mov_b64 s[4:5], -1
	s_cbranch_vccnz .LBB0_1237
	v_lshlrev_b32_e32 v138, 16, v142
	v_and_b32_e32 v139, 0xffff0000, v142
	v_lshlrev_b32_e32 v140, 16, v143
	v_and_b32_e32 v141, 0xffff0000, v143
	v_lshlrev_b32_e32 v142, 16, v144
	v_and_b32_e32 v143, 0xffff0000, v144
	v_lshlrev_b32_e32 v144, 16, v145
	v_and_b32_e32 v145, 0xffff0000, v145
	s_cbranch_execz .LBB0_1238
	s_branch .LBB0_1239

.LBB0_1241:
	s_or_b64 exec, exec, s[12:13]
	v_or_b32_e32 v175, 16, v1
	v_add_u32_e32 v114, s9, v175
	s_waitcnt lgkmcnt(0)
	v_ashrrev_i32_e32 v115, 31, v114
	v_lshlrev_b64 v[138:139], 10, v[114:115]
	v_lshl_add_u64 v[122:123], v[138:139], 0, s[10:11]
	v_readlane_b32 s36, v251, 16
	v_or_b32_e32 v122, v122, v174
	v_readlane_b32 s50, v251, 30
	v_readlane_b32 s51, v251, 31
	s_mov_b64 s[12:13], -1
	s_and_b64 vcc, exec, s[0:1]
	v_lshl_add_u64 v[140:141], v[122:123], 1, s[50:51]
	v_readlane_b32 s37, v251, 17
	v_readlane_b32 s38, v251, 18
	v_readlane_b32 s39, v251, 19
	v_readlane_b32 s40, v251, 20
	v_readlane_b32 s41, v251, 21
	v_readlane_b32 s42, v251, 22
	v_readlane_b32 s43, v251, 23
	v_readlane_b32 s44, v251, 24
	v_readlane_b32 s45, v251, 25
	v_readlane_b32 s46, v251, 26
	v_readlane_b32 s47, v251, 27
	v_readlane_b32 s48, v251, 28
	v_readlane_b32 s49, v251, 29
	s_cbranch_vccnz .LBB0_1243
	global_load_dwordx4 v[118:121], v[140:141], off
	global_load_dwordx4 v[126:129], v[140:141], off offset:256
	s_mov_b64 s[12:13], 0
	s_waitcnt vmcnt(0)
	v_lshlrev_b32_e32 v114, 16, v118
	v_and_b32_e32 v115, 0xffff0000, v118
	v_lshlrev_b32_e32 v116, 16, v119
	v_and_b32_e32 v117, 0xffff0000, v119
	v_lshlrev_b32_e32 v118, 16, v120
	v_and_b32_e32 v119, 0xffff0000, v120
	v_lshlrev_b32_e32 v120, 16, v121
	v_and_b32_e32 v121, 0xffff0000, v121

.LBB0_1245:
	s_and_b64 vcc, exec, s[0:1]
	s_mov_b64 s[12:13], -1
	s_cbranch_vccnz .LBB0_1247
	v_lshlrev_b32_e32 v122, 16, v126
	v_and_b32_e32 v123, 0xffff0000, v126
	v_lshlrev_b32_e32 v124, 16, v127
	v_and_b32_e32 v125, 0xffff0000, v127
	v_lshlrev_b32_e32 v126, 16, v128
	v_and_b32_e32 v127, 0xffff0000, v128
	v_lshlrev_b32_e32 v128, 16, v129
	v_and_b32_e32 v129, 0xffff0000, v129
	s_cbranch_execz .LBB0_1248
	s_branch .LBB0_1249

.LBB0_1251:
	s_or_b64 exec, exec, s[12:13]
	v_or_b32_e32 v176, 32, v1
	v_add_u32_e32 v98, s9, v176
	s_waitcnt lgkmcnt(0)
	v_ashrrev_i32_e32 v99, 31, v98
	v_lshlrev_b64 v[122:123], 10, v[98:99]
	v_lshl_add_u64 v[106:107], v[122:123], 0, s[10:11]
	v_readlane_b32 s36, v251, 16
	v_or_b32_e32 v106, v106, v174
	v_readlane_b32 s50, v251, 30
	v_readlane_b32 s51, v251, 31
	s_mov_b64 s[12:13], -1
	s_and_b64 vcc, exec, s[0:1]
	v_lshl_add_u64 v[124:125], v[106:107], 1, s[50:51]
	v_readlane_b32 s37, v251, 17
	v_readlane_b32 s38, v251, 18
	v_readlane_b32 s39, v251, 19
	v_readlane_b32 s40, v251, 20
	v_readlane_b32 s41, v251, 21
	v_readlane_b32 s42, v251, 22
	v_readlane_b32 s43, v251, 23
	v_readlane_b32 s44, v251, 24
	v_readlane_b32 s45, v251, 25
	v_readlane_b32 s46, v251, 26
	v_readlane_b32 s47, v251, 27
	v_readlane_b32 s48, v251, 28
	v_readlane_b32 s49, v251, 29
	s_cbranch_vccnz .LBB0_1253
	global_load_dwordx4 v[102:105], v[124:125], off
	global_load_dwordx4 v[110:113], v[124:125], off offset:256
	s_mov_b64 s[12:13], 0
	s_waitcnt vmcnt(0)
	v_lshlrev_b32_e32 v98, 16, v102
	v_and_b32_e32 v99, 0xffff0000, v102
	v_lshlrev_b32_e32 v100, 16, v103
	v_and_b32_e32 v101, 0xffff0000, v103
	v_lshlrev_b32_e32 v102, 16, v104
	v_and_b32_e32 v103, 0xffff0000, v104
	v_lshlrev_b32_e32 v104, 16, v105
	v_and_b32_e32 v105, 0xffff0000, v105

.LBB0_1255:
	s_and_b64 vcc, exec, s[0:1]
	s_mov_b64 s[12:13], -1
	s_cbranch_vccnz .LBB0_1257
	v_lshlrev_b32_e32 v106, 16, v110
	v_and_b32_e32 v107, 0xffff0000, v110
	v_lshlrev_b32_e32 v108, 16, v111
	v_and_b32_e32 v109, 0xffff0000, v111
	v_lshlrev_b32_e32 v110, 16, v112
	v_and_b32_e32 v111, 0xffff0000, v112
	v_lshlrev_b32_e32 v112, 16, v113
	v_and_b32_e32 v113, 0xffff0000, v113
	s_cbranch_execz .LBB0_1258
	s_branch .LBB0_1259

.LBB0_1261:
	s_or_b64 exec, exec, s[12:13]
	v_or_b32_e32 v177, 48, v1
	v_add_u32_e32 v82, s9, v177
	s_waitcnt lgkmcnt(0)
	v_ashrrev_i32_e32 v83, 31, v82
	v_lshlrev_b64 v[106:107], 10, v[82:83]
	v_lshl_add_u64 v[90:91], v[106:107], 0, s[10:11]
	v_readlane_b32 s36, v251, 16
	v_or_b32_e32 v90, v90, v174
	v_readlane_b32 s50, v251, 30
	v_readlane_b32 s51, v251, 31
	s_mov_b64 s[12:13], -1
	s_and_b64 vcc, exec, s[0:1]
	v_lshl_add_u64 v[108:109], v[90:91], 1, s[50:51]
	v_readlane_b32 s37, v251, 17
	v_readlane_b32 s38, v251, 18
	v_readlane_b32 s39, v251, 19
	v_readlane_b32 s40, v251, 20
	v_readlane_b32 s41, v251, 21
	v_readlane_b32 s42, v251, 22
	v_readlane_b32 s43, v251, 23
	v_readlane_b32 s44, v251, 24
	v_readlane_b32 s45, v251, 25
	v_readlane_b32 s46, v251, 26
	v_readlane_b32 s47, v251, 27
	v_readlane_b32 s48, v251, 28
	v_readlane_b32 s49, v251, 29
	s_cbranch_vccnz .LBB0_1263
	global_load_dwordx4 v[86:89], v[108:109], off
	global_load_dwordx4 v[94:97], v[108:109], off offset:256
	s_mov_b64 s[12:13], 0
	s_waitcnt vmcnt(0)
	v_lshlrev_b32_e32 v82, 16, v86
	v_and_b32_e32 v83, 0xffff0000, v86
	v_lshlrev_b32_e32 v84, 16, v87
	v_and_b32_e32 v85, 0xffff0000, v87
	v_lshlrev_b32_e32 v86, 16, v88
	v_and_b32_e32 v87, 0xffff0000, v88
	v_lshlrev_b32_e32 v88, 16, v89
	v_and_b32_e32 v89, 0xffff0000, v89

.LBB0_1265:
	s_and_b64 vcc, exec, s[0:1]
	s_mov_b64 s[12:13], -1
	s_cbranch_vccnz .LBB0_1267
	v_lshlrev_b32_e32 v90, 16, v94
	v_and_b32_e32 v91, 0xffff0000, v94
	v_lshlrev_b32_e32 v92, 16, v95
	v_and_b32_e32 v93, 0xffff0000, v95
	v_lshlrev_b32_e32 v94, 16, v96
	v_and_b32_e32 v95, 0xffff0000, v96
	v_lshlrev_b32_e32 v96, 16, v97
	v_and_b32_e32 v97, 0xffff0000, v97
	s_cbranch_execz .LBB0_1268
	s_branch .LBB0_1269

.LBB0_1271:
	s_or_b64 exec, exec, s[12:13]
	v_add_u32_e32 v168, 0x80, v1
	v_add_u32_e32 v66, s9, v168
	s_waitcnt lgkmcnt(0)
	v_ashrrev_i32_e32 v67, 31, v66
	v_lshlrev_b64 v[90:91], 10, v[66:67]
	v_lshl_add_u64 v[74:75], v[90:91], 0, s[10:11]
	v_readlane_b32 s36, v251, 16
	v_or_b32_e32 v74, v74, v174
	v_readlane_b32 s50, v251, 30
	v_readlane_b32 s51, v251, 31
	s_mov_b64 s[12:13], -1
	s_and_b64 vcc, exec, s[0:1]
	v_lshl_add_u64 v[92:93], v[74:75], 1, s[50:51]
	v_readlane_b32 s37, v251, 17
	v_readlane_b32 s38, v251, 18
	v_readlane_b32 s39, v251, 19
	v_readlane_b32 s40, v251, 20
	v_readlane_b32 s41, v251, 21
	v_readlane_b32 s42, v251, 22
	v_readlane_b32 s43, v251, 23
	v_readlane_b32 s44, v251, 24
	v_readlane_b32 s45, v251, 25
	v_readlane_b32 s46, v251, 26
	v_readlane_b32 s47, v251, 27
	v_readlane_b32 s48, v251, 28
	v_readlane_b32 s49, v251, 29
	s_cbranch_vccnz .LBB0_1273
	global_load_dwordx4 v[70:73], v[92:93], off
	global_load_dwordx4 v[78:81], v[92:93], off offset:256
	s_mov_b64 s[12:13], 0
	s_waitcnt vmcnt(0)
	v_lshlrev_b32_e32 v66, 16, v70
	v_and_b32_e32 v67, 0xffff0000, v70
	v_lshlrev_b32_e32 v68, 16, v71
	v_and_b32_e32 v69, 0xffff0000, v71
	v_lshlrev_b32_e32 v70, 16, v72
	v_and_b32_e32 v71, 0xffff0000, v72
	v_lshlrev_b32_e32 v72, 16, v73
	v_and_b32_e32 v73, 0xffff0000, v73

.LBB0_1275:
	s_and_b64 vcc, exec, s[0:1]
	s_mov_b64 s[12:13], -1
	s_cbranch_vccnz .LBB0_1277
	v_lshlrev_b32_e32 v74, 16, v78
	v_and_b32_e32 v75, 0xffff0000, v78
	v_lshlrev_b32_e32 v76, 16, v79
	v_and_b32_e32 v77, 0xffff0000, v79
	v_lshlrev_b32_e32 v78, 16, v80
	v_and_b32_e32 v79, 0xffff0000, v80
	v_lshlrev_b32_e32 v80, 16, v81
	v_and_b32_e32 v81, 0xffff0000, v81
	s_cbranch_execz .LBB0_1278
	s_branch .LBB0_1279

.LBB0_1281:
	s_or_b64 exec, exec, s[12:13]
	v_add_u32_e32 v170, 0x90, v1
	v_add_u32_e32 v50, s9, v170
	s_waitcnt lgkmcnt(0)
	v_ashrrev_i32_e32 v51, 31, v50
	v_lshlrev_b64 v[74:75], 10, v[50:51]
	v_lshl_add_u64 v[58:59], v[74:75], 0, s[10:11]
	v_readlane_b32 s36, v251, 16
	v_or_b32_e32 v58, v58, v174
	v_readlane_b32 s50, v251, 30
	v_readlane_b32 s51, v251, 31
	s_mov_b64 s[12:13], -1
	s_and_b64 vcc, exec, s[0:1]
	v_lshl_add_u64 v[76:77], v[58:59], 1, s[50:51]
	v_readlane_b32 s37, v251, 17
	v_readlane_b32 s38, v251, 18
	v_readlane_b32 s39, v251, 19
	v_readlane_b32 s40, v251, 20
	v_readlane_b32 s41, v251, 21
	v_readlane_b32 s42, v251, 22
	v_readlane_b32 s43, v251, 23
	v_readlane_b32 s44, v251, 24
	v_readlane_b32 s45, v251, 25
	v_readlane_b32 s46, v251, 26
	v_readlane_b32 s47, v251, 27
	v_readlane_b32 s48, v251, 28
	v_readlane_b32 s49, v251, 29
	s_cbranch_vccnz .LBB0_1283
	global_load_dwordx4 v[54:57], v[76:77], off
	global_load_dwordx4 v[62:65], v[76:77], off offset:256
	s_mov_b64 s[12:13], 0
	s_waitcnt vmcnt(0)
	v_lshlrev_b32_e32 v50, 16, v54
	v_and_b32_e32 v51, 0xffff0000, v54
	v_lshlrev_b32_e32 v52, 16, v55
	v_and_b32_e32 v53, 0xffff0000, v55
	v_lshlrev_b32_e32 v54, 16, v56
	v_and_b32_e32 v55, 0xffff0000, v56
	v_lshlrev_b32_e32 v56, 16, v57
	v_and_b32_e32 v57, 0xffff0000, v57

.LBB0_1285:
	s_and_b64 vcc, exec, s[0:1]
	s_mov_b64 s[12:13], -1
	s_cbranch_vccnz .LBB0_1287
	v_lshlrev_b32_e32 v58, 16, v62
	v_and_b32_e32 v59, 0xffff0000, v62
	v_lshlrev_b32_e32 v60, 16, v63
	v_and_b32_e32 v61, 0xffff0000, v63
	v_lshlrev_b32_e32 v62, 16, v64
	v_and_b32_e32 v63, 0xffff0000, v64
	v_lshlrev_b32_e32 v64, 16, v65
	v_and_b32_e32 v65, 0xffff0000, v65
	s_cbranch_execz .LBB0_1288
	s_branch .LBB0_1289

.LBB0_1291:
	s_or_b64 exec, exec, s[12:13]
	v_add_u32_e32 v180, 0xa0, v1
	v_add_u32_e32 v34, s9, v180
	s_waitcnt lgkmcnt(0)
	v_ashrrev_i32_e32 v35, 31, v34
	v_lshlrev_b64 v[58:59], 10, v[34:35]
	v_lshl_add_u64 v[42:43], v[58:59], 0, s[10:11]
	v_readlane_b32 s36, v251, 16
	v_or_b32_e32 v42, v42, v174
	v_readlane_b32 s50, v251, 30
	v_readlane_b32 s51, v251, 31
	s_mov_b64 s[12:13], -1
	s_and_b64 vcc, exec, s[0:1]
	v_lshl_add_u64 v[60:61], v[42:43], 1, s[50:51]
	v_readlane_b32 s37, v251, 17
	v_readlane_b32 s38, v251, 18
	v_readlane_b32 s39, v251, 19
	v_readlane_b32 s40, v251, 20
	v_readlane_b32 s41, v251, 21
	v_readlane_b32 s42, v251, 22
	v_readlane_b32 s43, v251, 23
	v_readlane_b32 s44, v251, 24
	v_readlane_b32 s45, v251, 25
	v_readlane_b32 s46, v251, 26
	v_readlane_b32 s47, v251, 27
	v_readlane_b32 s48, v251, 28
	v_readlane_b32 s49, v251, 29
	s_cbranch_vccnz .LBB0_1293
	global_load_dwordx4 v[38:41], v[60:61], off
	global_load_dwordx4 v[46:49], v[60:61], off offset:256
	s_mov_b64 s[12:13], 0
	s_waitcnt vmcnt(0)
	v_lshlrev_b32_e32 v34, 16, v38
	v_and_b32_e32 v35, 0xffff0000, v38
	v_lshlrev_b32_e32 v36, 16, v39
	v_and_b32_e32 v37, 0xffff0000, v39
	v_lshlrev_b32_e32 v38, 16, v40
	v_and_b32_e32 v39, 0xffff0000, v40
	v_lshlrev_b32_e32 v40, 16, v41
	v_and_b32_e32 v41, 0xffff0000, v41

.LBB0_1295:
	s_and_b64 vcc, exec, s[0:1]
	s_mov_b64 s[12:13], -1
	s_cbranch_vccnz .LBB0_1297
	v_lshlrev_b32_e32 v42, 16, v46
	v_and_b32_e32 v43, 0xffff0000, v46
	v_lshlrev_b32_e32 v44, 16, v47
	v_and_b32_e32 v45, 0xffff0000, v47
	v_lshlrev_b32_e32 v46, 16, v48
	v_and_b32_e32 v47, 0xffff0000, v48
	v_lshlrev_b32_e32 v48, 16, v49
	v_and_b32_e32 v49, 0xffff0000, v49
	s_cbranch_execz .LBB0_1298
	s_branch .LBB0_1299

.LBB0_1301:
	s_or_b64 exec, exec, s[12:13]
	v_add_u32_e32 v48, 0xb0, v1
	v_add_u32_e32 v18, s9, v48
	s_waitcnt lgkmcnt(0)
	v_ashrrev_i32_e32 v19, 31, v18
	v_lshlrev_b64 v[42:43], 10, v[18:19]
	v_lshl_add_u64 v[26:27], v[42:43], 0, s[10:11]
	v_readlane_b32 s36, v251, 16
	v_or_b32_e32 v26, v26, v174
	v_readlane_b32 s50, v251, 30
	v_readlane_b32 s51, v251, 31
	s_mov_b64 s[12:13], -1
	s_and_b64 vcc, exec, s[0:1]
	v_lshl_add_u64 v[44:45], v[26:27], 1, s[50:51]
	v_readlane_b32 s37, v251, 17
	v_readlane_b32 s38, v251, 18
	v_readlane_b32 s39, v251, 19
	v_readlane_b32 s40, v251, 20
	v_readlane_b32 s41, v251, 21
	v_readlane_b32 s42, v251, 22
	v_readlane_b32 s43, v251, 23
	v_readlane_b32 s44, v251, 24
	v_readlane_b32 s45, v251, 25
	v_readlane_b32 s46, v251, 26
	v_readlane_b32 s47, v251, 27
	v_readlane_b32 s48, v251, 28
	v_readlane_b32 s49, v251, 29
	s_cbranch_vccnz .LBB0_1303
	global_load_dwordx4 v[22:25], v[44:45], off
	global_load_dwordx4 v[30:33], v[44:45], off offset:256
	s_mov_b64 s[12:13], 0
	s_waitcnt vmcnt(0)
	v_lshlrev_b32_e32 v18, 16, v22
	v_and_b32_e32 v19, 0xffff0000, v22
	v_lshlrev_b32_e32 v20, 16, v23
	v_and_b32_e32 v21, 0xffff0000, v23
	v_lshlrev_b32_e32 v22, 16, v24
	v_and_b32_e32 v23, 0xffff0000, v24
	v_lshlrev_b32_e32 v24, 16, v25
	v_and_b32_e32 v25, 0xffff0000, v25

.LBB0_1305:
	s_and_b64 vcc, exec, s[0:1]
	s_mov_b64 s[12:13], -1
	s_cbranch_vccnz .LBB0_1307
	v_lshlrev_b32_e32 v26, 16, v30
	v_and_b32_e32 v27, 0xffff0000, v30
	v_lshlrev_b32_e32 v28, 16, v31
	v_and_b32_e32 v29, 0xffff0000, v31
	v_lshlrev_b32_e32 v30, 16, v32
	v_and_b32_e32 v31, 0xffff0000, v32
	v_lshlrev_b32_e32 v32, 16, v33
	v_and_b32_e32 v33, 0xffff0000, v33
	s_cbranch_execz .LBB0_1308
	s_branch .LBB0_1309
